# EpiRes phase prologue: dropped the vmcnt(0) in front of the residual unpack (residual already complete by the earlier counted wait), unpack VALU now runs under the A/B LDS-DMA loads
# speedup vs baseline: 1.0011x; 1.0011x over previous
.LBB0_592:
	s_add_i32 m0, s68, 0x18000
	v_lshl_add_u64 v[64:65], v[64:65], 0, s[70:71]
	s_waitcnt vmcnt(4)
	s_barrier
	global_load_lds_dwordx4 v[64:65], off
	v_lshl_add_u64 v[64:65], v[66:67], 0, s[70:71]
	s_add_i32 m0, s68, 0x1a000
	s_add_i32 s79, s68, 0x8000
	global_load_lds_dwordx4 v[64:65], off
	v_lshl_add_u64 v[64:65], v[68:69], 0, s[70:71]
	s_mov_b32 m0, s79
	s_add_i32 s80, s68, 0xa000
	global_load_lds_dwordx4 v[64:65], off
	v_lshl_add_u64 v[64:65], v[70:71], 0, s[70:71]
	s_mov_b32 m0, s80
	v_or_b32_e32 v146, s7, v76
	global_load_lds_dwordx4 v[64:65], off
	s_add_i32 m0, s68, 0x1c000
	v_lshl_add_u64 v[64:65], v[72:73], 0, s[70:71]
	global_load_lds_dwordx4 v[64:65], off
	v_lshl_add_u64 v[64:65], v[74:75], 0, s[70:71]
	s_add_i32 m0, s68, 0x1e000
	v_lshlrev_b32_e32 v77, 4, v139
	global_load_lds_dwordx4 v[64:65], off
	v_lshlrev_b32_e32 v78, 6, v146
	s_movk_i32 s7, 0x3c0
	v_lshlrev_b32_e32 v79, 2, v146
	v_and_or_b32 v78, v78, s7, v77
	s_lshl_b32 s6, s6, 13
	v_and_b32_e32 v79, 32, v79
	v_lshl_or_b32 v77, v76, 6, v77
	v_lshlrev_b32_e32 v76, 2, v76
	v_bitop3_b32 v149, v78, s6, v79 bitop3:0xde
	s_lshl_b32 s6, s87, 12
	v_and_b32_e32 v76, 32, v76
	v_bitop3_b32 v147, v77, s6, v76 bitop3:0xde
	v_div_scale_f32 v66, s[6:7], s16, s16, 1.0
	v_rcp_f32_e32 v67, v66
	s_lshr_b32 s78, s17, 6
	s_add_i32 s81, s78, -2
	s_ashr_i32 s84, s39, 31
	v_fma_f32 v64, -v66, v67, 1.0
	v_fmac_f32_e32 v67, v64, v67
	v_div_scale_f32 v64, vcc, 1.0, s16, 1.0
	v_mul_f32_e32 v65, v64, v67
	v_fma_f32 v68, -v66, v65, v64
	v_fmac_f32_e32 v65, v68, v67
	v_fma_f32 v64, -v66, v65, v64
	v_div_fmas_f32 v64, v64, v67, v65
	v_div_fixup_f32 v136, v64, s16, 1.0
	v_lshlrev_b32_e32 v64, 16, v62
	v_and_b32_e32 v65, 0xffff0000, v62
	v_mov_b32_e32 v137, v136
	v_lshlrev_b32_e32 v62, 16, v63
	v_and_b32_e32 v63, 0xffff0000, v63
	v_pk_mul_f32 v[126:127], v[136:137], v[62:63] op_sel_hi:[0,1]
	v_lshlrev_b32_e32 v62, 16, v60
	v_and_b32_e32 v63, 0xffff0000, v60
	v_lshlrev_b32_e32 v60, 16, v61
	v_and_b32_e32 v61, 0xffff0000, v61
	v_pk_mul_f32 v[122:123], v[136:137], v[60:61] op_sel_hi:[0,1]
	v_lshlrev_b32_e32 v60, 16, v58
	v_and_b32_e32 v61, 0xffff0000, v58
	v_lshlrev_b32_e32 v58, 16, v59
	v_and_b32_e32 v59, 0xffff0000, v59
	v_pk_mul_f32 v[118:119], v[136:137], v[58:59] op_sel_hi:[0,1]
	v_lshlrev_b32_e32 v58, 16, v56
	v_and_b32_e32 v59, 0xffff0000, v56
	v_lshlrev_b32_e32 v56, 16, v57
	v_and_b32_e32 v57, 0xffff0000, v57
	v_pk_mul_f32 v[114:115], v[136:137], v[56:57] op_sel_hi:[0,1]
	v_lshlrev_b32_e32 v56, 16, v54
	v_and_b32_e32 v57, 0xffff0000, v54
	v_lshlrev_b32_e32 v54, 16, v55
	v_and_b32_e32 v55, 0xffff0000, v55
	v_pk_mul_f32 v[110:111], v[136:137], v[54:55] op_sel_hi:[0,1]
	v_lshlrev_b32_e32 v54, 16, v52
	v_and_b32_e32 v55, 0xffff0000, v52
	v_lshlrev_b32_e32 v52, 16, v53
	v_and_b32_e32 v53, 0xffff0000, v53
	s_waitcnt lgkmcnt(0)
	v_pk_mul_f32 v[106:107], v[136:137], v[52:53] op_sel_hi:[0,1]
	v_lshlrev_b32_e32 v52, 16, v50
	v_and_b32_e32 v53, 0xffff0000, v50
	v_lshlrev_b32_e32 v50, 16, v51
	v_and_b32_e32 v51, 0xffff0000, v51
	v_pk_mul_f32 v[102:103], v[136:137], v[50:51] op_sel_hi:[0,1]
	v_lshlrev_b32_e32 v50, 16, v48
	v_and_b32_e32 v51, 0xffff0000, v48
	v_lshlrev_b32_e32 v48, 16, v49
	v_and_b32_e32 v49, 0xffff0000, v49
	v_pk_mul_f32 v[98:99], v[136:137], v[48:49] op_sel_hi:[0,1]
	v_lshlrev_b32_e32 v48, 16, v46
	v_and_b32_e32 v49, 0xffff0000, v46
	v_lshlrev_b32_e32 v46, 16, v47
	v_and_b32_e32 v47, 0xffff0000, v47
	v_pk_mul_f32 v[94:95], v[136:137], v[46:47] op_sel_hi:[0,1]
	v_lshlrev_b32_e32 v46, 16, v44
	v_and_b32_e32 v47, 0xffff0000, v44
	v_lshlrev_b32_e32 v44, 16, v45
	v_and_b32_e32 v45, 0xffff0000, v45
	v_pk_mul_f32 v[90:91], v[136:137], v[44:45] op_sel_hi:[0,1]
	v_lshlrev_b32_e32 v44, 16, v42
	v_and_b32_e32 v45, 0xffff0000, v42
	v_lshlrev_b32_e32 v42, 16, v43
	v_and_b32_e32 v43, 0xffff0000, v43
	v_pk_mul_f32 v[86:87], v[136:137], v[42:43] op_sel_hi:[0,1]
	v_lshlrev_b32_e32 v42, 16, v40
	v_and_b32_e32 v43, 0xffff0000, v40
	v_lshlrev_b32_e32 v40, 16, v41
	v_and_b32_e32 v41, 0xffff0000, v41
	v_pk_mul_f32 v[82:83], v[136:137], v[40:41] op_sel_hi:[0,1]
	v_lshlrev_b32_e32 v40, 16, v38
	v_and_b32_e32 v41, 0xffff0000, v38
	v_lshlrev_b32_e32 v38, 16, v39
	v_and_b32_e32 v39, 0xffff0000, v39
	v_pk_mul_f32 v[78:79], v[136:137], v[38:39] op_sel_hi:[0,1]
	v_lshlrev_b32_e32 v38, 16, v36
	v_and_b32_e32 v39, 0xffff0000, v36
	v_lshlrev_b32_e32 v36, 16, v37
	v_and_b32_e32 v37, 0xffff0000, v37
	v_pk_mul_f32 v[74:75], v[136:137], v[36:37] op_sel_hi:[0,1]
	v_lshlrev_b32_e32 v36, 16, v34
	v_and_b32_e32 v37, 0xffff0000, v34
	v_lshlrev_b32_e32 v34, 16, v35
	v_and_b32_e32 v35, 0xffff0000, v35
	v_pk_mul_f32 v[70:71], v[136:137], v[34:35] op_sel_hi:[0,1]
	v_lshlrev_b32_e32 v34, 16, v32
	v_and_b32_e32 v35, 0xffff0000, v32
	v_lshlrev_b32_e32 v32, 16, v33
	v_and_b32_e32 v33, 0xffff0000, v33
	v_pk_mul_f32 v[66:67], v[136:137], v[32:33] op_sel_hi:[0,1]
	v_lshlrev_b32_e32 v32, 16, v30
	v_and_b32_e32 v33, 0xffff0000, v30
	v_lshlrev_b32_e32 v30, 16, v31
	v_and_b32_e32 v31, 0xffff0000, v31
	v_pk_mul_f32 v[120:121], v[136:137], v[62:63] op_sel_hi:[0,1]
	v_pk_mul_f32 v[62:63], v[136:137], v[30:31] op_sel_hi:[0,1]
	v_lshlrev_b32_e32 v30, 16, v28
	v_and_b32_e32 v31, 0xffff0000, v28
	v_lshlrev_b32_e32 v28, 16, v29
	v_and_b32_e32 v29, 0xffff0000, v29
	v_pk_mul_f32 v[112:113], v[136:137], v[58:59] op_sel_hi:[0,1]
	v_pk_mul_f32 v[58:59], v[136:137], v[28:29] op_sel_hi:[0,1]
	v_lshlrev_b32_e32 v28, 16, v26
	v_and_b32_e32 v29, 0xffff0000, v26
	v_lshlrev_b32_e32 v26, 16, v27
	v_and_b32_e32 v27, 0xffff0000, v27
	v_pk_mul_f32 v[104:105], v[136:137], v[54:55] op_sel_hi:[0,1]
	v_pk_mul_f32 v[54:55], v[136:137], v[26:27] op_sel_hi:[0,1]
	v_lshlrev_b32_e32 v26, 16, v24
	v_and_b32_e32 v27, 0xffff0000, v24
	v_lshlrev_b32_e32 v24, 16, v25
	v_and_b32_e32 v25, 0xffff0000, v25
	v_pk_mul_f32 v[96:97], v[136:137], v[50:51] op_sel_hi:[0,1]
	v_pk_mul_f32 v[50:51], v[136:137], v[24:25] op_sel_hi:[0,1]
	v_lshlrev_b32_e32 v24, 16, v22
	v_and_b32_e32 v25, 0xffff0000, v22
	v_lshlrev_b32_e32 v22, 16, v23
	v_and_b32_e32 v23, 0xffff0000, v23
	v_pk_mul_f32 v[88:89], v[136:137], v[46:47] op_sel_hi:[0,1]
	v_pk_mul_f32 v[46:47], v[136:137], v[22:23] op_sel_hi:[0,1]
	v_lshlrev_b32_e32 v22, 16, v20
	v_and_b32_e32 v23, 0xffff0000, v20
	v_lshlrev_b32_e32 v20, 16, v21
	v_and_b32_e32 v21, 0xffff0000, v21
	v_pk_mul_f32 v[80:81], v[136:137], v[42:43] op_sel_hi:[0,1]
	v_pk_mul_f32 v[42:43], v[136:137], v[20:21] op_sel_hi:[0,1]
	v_lshlrev_b32_e32 v20, 16, v18
	v_and_b32_e32 v21, 0xffff0000, v18
	v_lshlrev_b32_e32 v18, 16, v19
	v_and_b32_e32 v19, 0xffff0000, v19
	v_pk_mul_f32 v[72:73], v[136:137], v[38:39] op_sel_hi:[0,1]
	v_pk_mul_f32 v[38:39], v[136:137], v[18:19] op_sel_hi:[0,1]
	v_lshlrev_b32_e32 v18, 16, v16
	v_and_b32_e32 v19, 0xffff0000, v16
	v_lshlrev_b32_e32 v16, 16, v17
	v_and_b32_e32 v17, 0xffff0000, v17
	v_pk_mul_f32 v[124:125], v[136:137], v[64:65] op_sel_hi:[0,1]
	v_pk_mul_f32 v[64:65], v[136:137], v[34:35] op_sel_hi:[0,1]
	v_pk_mul_f32 v[34:35], v[136:137], v[16:17] op_sel_hi:[0,1]
	v_lshlrev_b32_e32 v16, 16, v14
	v_and_b32_e32 v17, 0xffff0000, v14
	v_lshlrev_b32_e32 v14, 16, v15
	v_and_b32_e32 v15, 0xffff0000, v15
	v_pk_mul_f32 v[108:109], v[136:137], v[56:57] op_sel_hi:[0,1]
	v_pk_mul_f32 v[56:57], v[136:137], v[30:31] op_sel_hi:[0,1]
	v_pk_mul_f32 v[30:31], v[136:137], v[14:15] op_sel_hi:[0,1]
	v_lshlrev_b32_e32 v14, 16, v12
	v_and_b32_e32 v15, 0xffff0000, v12
	v_lshlrev_b32_e32 v12, 16, v13
	v_and_b32_e32 v13, 0xffff0000, v13
	v_pk_mul_f32 v[92:93], v[136:137], v[48:49] op_sel_hi:[0,1]
	v_pk_mul_f32 v[48:49], v[136:137], v[26:27] op_sel_hi:[0,1]
	v_pk_mul_f32 v[26:27], v[136:137], v[12:13] op_sel_hi:[0,1]
	v_lshlrev_b32_e32 v12, 16, v10
	v_and_b32_e32 v13, 0xffff0000, v10
	v_lshlrev_b32_e32 v10, 16, v11
	v_and_b32_e32 v11, 0xffff0000, v11
	v_pk_mul_f32 v[76:77], v[136:137], v[40:41] op_sel_hi:[0,1]
	v_pk_mul_f32 v[40:41], v[136:137], v[22:23] op_sel_hi:[0,1]
	v_pk_mul_f32 v[22:23], v[136:137], v[10:11] op_sel_hi:[0,1]
	v_lshlrev_b32_e32 v10, 16, v8
	v_and_b32_e32 v11, 0xffff0000, v8
	v_lshlrev_b32_e32 v8, 16, v9
	v_and_b32_e32 v9, 0xffff0000, v9
	v_pk_mul_f32 v[116:117], v[136:137], v[60:61] op_sel_hi:[0,1]
	v_pk_mul_f32 v[60:61], v[136:137], v[32:33] op_sel_hi:[0,1]
	v_pk_mul_f32 v[32:33], v[136:137], v[18:19] op_sel_hi:[0,1]
	v_pk_mul_f32 v[18:19], v[136:137], v[8:9] op_sel_hi:[0,1]
	v_lshlrev_b32_e32 v8, 16, v6
	v_and_b32_e32 v9, 0xffff0000, v6
	v_lshlrev_b32_e32 v6, 16, v7
	v_and_b32_e32 v7, 0xffff0000, v7
	v_pk_mul_f32 v[84:85], v[136:137], v[44:45] op_sel_hi:[0,1]
	v_pk_mul_f32 v[44:45], v[136:137], v[24:25] op_sel_hi:[0,1]
	v_pk_mul_f32 v[24:25], v[136:137], v[14:15] op_sel_hi:[0,1]
	v_pk_mul_f32 v[14:15], v[136:137], v[6:7] op_sel_hi:[0,1]
	v_lshlrev_b32_e32 v6, 16, v4
	v_and_b32_e32 v7, 0xffff0000, v4
	v_lshlrev_b32_e32 v4, 16, v5
	v_and_b32_e32 v5, 0xffff0000, v5
	v_add_u32_e32 v138, v141, v138
	s_waitcnt vmcnt(6)
	v_pk_mul_f32 v[100:101], v[136:137], v[52:53] op_sel_hi:[0,1]
	v_pk_mul_f32 v[52:53], v[136:137], v[28:29] op_sel_hi:[0,1]
	v_pk_mul_f32 v[28:29], v[136:137], v[16:17] op_sel_hi:[0,1]
	v_pk_mul_f32 v[16:17], v[136:137], v[10:11] op_sel_hi:[0,1]
	v_pk_mul_f32 v[10:11], v[136:137], v[4:5] op_sel_hi:[0,1]
	v_lshlrev_b32_e32 v4, 16, v0
	v_and_b32_e32 v5, 0xffff0000, v0
	v_lshlrev_b32_e32 v0, 16, v1
	v_and_b32_e32 v1, 0xffff0000, v1
	s_cmp_eq_u64 s[28:29], 0
	v_add_lshl_u32 v158, v138, v140, 1
	v_add_u32_e32 v140, v144, v142
	v_pk_mul_f32 v[68:69], v[136:137], v[36:37] op_sel_hi:[0,1]
	v_pk_mul_f32 v[36:37], v[136:137], v[20:21] op_sel_hi:[0,1]
	v_pk_mul_f32 v[20:21], v[136:137], v[12:13] op_sel_hi:[0,1]
	v_pk_mul_f32 v[12:13], v[136:137], v[8:9] op_sel_hi:[0,1]
	v_pk_mul_f32 v[8:9], v[136:137], v[6:7] op_sel_hi:[0,1]
	v_pk_mul_f32 v[6:7], v[136:137], v[0:1] op_sel_hi:[0,1]
	v_lshlrev_b32_e32 v0, 16, v2
	v_and_b32_e32 v1, 0xffff0000, v2
	v_lshlrev_b32_e32 v2, 16, v3
	v_and_b32_e32 v3, 0xffff0000, v3
	v_cmp_eq_u32_e64 s[6:7], 0, v139
	s_cselect_b64 s[20:21], -1, 0
	s_cmp_lg_u64 s[28:29], 0
	v_lshl_add_u64 v[138:139], s[22:23], 0, v[158:159]
	v_add_lshl_u32 v158, v140, v143, 1
	v_pk_mul_f32 v[4:5], v[136:137], v[4:5] op_sel_hi:[0,1]
	v_pk_mul_f32 v[0:1], v[136:137], v[0:1] op_sel_hi:[0,1]
	v_pk_mul_f32 v[2:3], v[136:137], v[2:3] op_sel_hi:[0,1]
	s_mov_b32 s43, 0
	s_mov_b32 s17, s16
	s_mov_b32 s18, s16
	s_mov_b32 s19, s16
	s_cselect_b64 s[58:59], -1, 0
	s_mov_b32 s31, s27
	s_and_b32 s29, s29, 0xffff
	s_and_b32 s25, s97, 0xffff
	s_mov_b32 s24, s96
	v_or_b32_e32 v148, s8, v145
	v_lshl_add_u64 v[140:141], s[22:23], 0, v[158:159]
	v_add_u32_e32 v149, 0, v149
	s_barrier
	s_branch .LBB0_594
